# rwkv tiles: branch-free fast path for the next-chunk prefetch address/load code when all staged rows are in range
# speedup vs baseline: 1.0109x; 1.0109x over previous
.LBB0_1411:
	s_add_i32 s52, s28, 1
	s_cmpk_eq_i32 s28, 0x87
	s_cbranch_scc1 .Lrw_du_nopf
	s_lshl_b32 s53, s52, 5
	s_sub_i32 s54, 0x11e0, s53
	s_and_b64 s[50:51], s[36:37], exec
	s_cselect_b32 s53, s53, s54
	s_add_i32 s54, s53, -1
	s_cmpk_eq_u32 s52, 0x87
	s_cbranch_scc1 .Lrw_du_pfslow
	s_and_saveexec_b64 s[50:51], s[42:43]
	v_add_u32_e32 v32, s54, v97
	v_lshlrev_b32_e32 v32, 11, v32
	v_mov_b32_e32 v33, v164
	v_lshl_add_u64 v[32:33], v[80:81], 0, v[32:33]
	global_load_dwordx4 v[32:35], v[32:33], off
	v_add_u32_e32 v28, s54, v98
	v_lshlrev_b32_e32 v28, 11, v28
	v_mov_b32_e32 v29, v164
	v_lshl_add_u64 v[28:29], v[80:81], 0, v[28:29]
	global_load_dwordx4 v[28:31], v[28:29], off
	v_add_u32_e32 v36, s54, v99
	v_lshlrev_b32_e32 v36, 11, v36
	v_mov_b32_e32 v37, v164
	v_lshl_add_u64 v[36:37], v[80:81], 0, v[36:37]
	global_load_dwordx4 v[36:39], v[36:37], off
	v_add_u32_e32 v44, s53, v97
	v_mov_b32_e32 v45, v164
	v_lshlrev_b64 v[44:45], 10, v[44:45]
	v_lshl_add_u64 v[44:45], v[82:83], 0, v[44:45]
	global_load_dwordx4 v[44:47], v[44:45], off
	v_add_u32_e32 v48, s53, v98
	v_mov_b32_e32 v49, v164
	v_lshlrev_b64 v[48:49], 10, v[48:49]
	v_lshl_add_u64 v[48:49], v[82:83], 0, v[48:49]
	global_load_dwordx4 v[48:51], v[48:49], off
	v_add_u32_e32 v52, s53, v99
	v_mov_b32_e32 v53, v164
	v_lshlrev_b64 v[52:53], 10, v[52:53]
	v_lshl_add_u64 v[52:53], v[82:83], 0, v[52:53]
	global_load_dwordx4 v[52:55], v[52:53], off
	s_mov_b64 exec, s[50:51]
	s_and_b64 exec, exec, s[44:45]
	v_add_u32_e32 v40, s54, v100
	v_lshlrev_b32_e32 v40, 11, v40
	v_mov_b32_e32 v41, v164
	v_lshl_add_u64 v[40:41], v[80:81], 0, v[40:41]
	global_load_dwordx4 v[40:43], v[40:41], off
	s_mov_b64 exec, s[50:51]
	s_and_b64 exec, exec, s[46:47]
	v_add_u32_e32 v56, s53, v100
	v_mov_b32_e32 v57, v164
	v_lshlrev_b64 v[56:57], 10, v[56:57]
	v_lshl_add_u64 v[56:57], v[82:83], 0, v[56:57]
	global_load_dwordx4 v[56:59], v[56:57], off
	s_mov_b64 exec, s[50:51]
	s_branch .Lrw_du_nopf
.Lrw_du_pfslow:
	v_add_u32_e32 v30, s54, v97
	v_add_u32_e32 v28, 0xffffff00, v30
	v_cmp_gt_u32_e32 vcc, s31, v28
	v_mov_b32_e32 v28, v164
	v_mov_b32_e32 v29, v164
	s_and_b64 s[56:57], s[42:43], vcc
	v_mov_b64_e32 v[32:33], v[28:29]
	v_mov_b64_e32 v[34:35], v[28:29]
	s_and_saveexec_b64 s[50:51], s[56:57]
	s_cbranch_execz .LBB0_1414
	v_lshlrev_b32_e32 v30, 11, v30
	v_mov_b32_e32 v31, v164
	v_lshl_add_u64 v[30:31], v[80:81], 0, v[30:31]
	global_load_dwordx4 v[32:35], v[30:31], off

.LBB0_1468:
	s_add_i32 s56, s28, 1
	v_readlane_b32 s0, v254, 14
	s_cmp_ge_u32 s56, s0
	s_cbranch_scc1 .Lrw_nd_nopf
	s_lshl_b32 s57, s56, 5
	s_sub_i32 s58, 0xe0, s57
	s_and_b64 s[50:51], s[36:37], exec
	s_cselect_b32 s64, s57, s58
	s_sub_i32 s58, 0x11e0, s57
	s_and_b64 s[50:51], s[36:37], exec
	s_cselect_b32 s50, s57, s58
	s_cmp_lt_u32 s28, 7
	s_movk_i32 s0, 0x10ff
	s_cselect_b32 s57, s64, s50
	s_cselect_b32 s58, 0xff, s0
	s_cselect_b32 s59, 0, 0x100
	s_add_i32 s66, s57, -1
	s_cmp_eq_u32 s56, 7
	s_cbranch_scc1 .Lrw_nd_pfslow
	s_cmp_eq_u32 s56, 8
	s_cbranch_scc1 .Lrw_nd_pfslow
	s_cmpk_eq_u32 s56, 0x87
	s_cbranch_scc1 .Lrw_nd_pfslow
	s_and_saveexec_b64 s[50:51], s[42:43]
	v_add_u32_e32 v32, s66, v93
	v_lshlrev_b32_e32 v32, 11, v32
	v_mov_b32_e32 v33, v164
	v_lshl_add_u64 v[32:33], v[84:85], 0, v[32:33]
	global_load_dwordx4 v[32:35], v[32:33], off
	v_add_u32_e32 v28, s66, v94
	v_lshlrev_b32_e32 v28, 11, v28
	v_mov_b32_e32 v29, v164
	v_lshl_add_u64 v[28:29], v[84:85], 0, v[28:29]
	global_load_dwordx4 v[28:31], v[28:29], off
	v_add_u32_e32 v36, s66, v95
	v_lshlrev_b32_e32 v36, 11, v36
	v_mov_b32_e32 v37, v164
	v_lshl_add_u64 v[36:37], v[84:85], 0, v[36:37]
	global_load_dwordx4 v[36:39], v[36:37], off
	v_add_u32_e32 v44, s57, v93
	v_mov_b32_e32 v45, v164
	v_lshlrev_b64 v[44:45], 10, v[44:45]
	v_lshl_add_u64 v[44:45], v[86:87], 0, v[44:45]
	global_load_dwordx4 v[44:47], v[44:45], off
	v_add_u32_e32 v48, s57, v94
	v_mov_b32_e32 v49, v164
	v_lshlrev_b64 v[48:49], 10, v[48:49]
	v_lshl_add_u64 v[48:49], v[86:87], 0, v[48:49]
	global_load_dwordx4 v[48:51], v[48:49], off
	v_add_u32_e32 v52, s57, v95
	v_mov_b32_e32 v53, v164
	v_lshlrev_b64 v[52:53], 10, v[52:53]
	v_lshl_add_u64 v[52:53], v[86:87], 0, v[52:53]
	global_load_dwordx4 v[52:55], v[52:53], off
	s_mov_b64 exec, s[50:51]
	s_andn2_b64 exec, exec, s[46:47]
	v_add_u32_e32 v40, s66, v96
	v_lshlrev_b32_e32 v40, 11, v40
	v_mov_b32_e32 v41, v164
	v_lshl_add_u64 v[40:41], v[84:85], 0, v[40:41]
	global_load_dwordx4 v[40:43], v[40:41], off
	s_mov_b64 exec, s[50:51]
	s_and_b64 exec, exec, s[48:49]
	v_add_u32_e32 v56, s57, v96
	v_mov_b32_e32 v57, v164
	v_lshlrev_b64 v[56:57], 10, v[56:57]
	v_lshl_add_u64 v[56:57], v[86:87], 0, v[56:57]
	global_load_dwordx4 v[56:59], v[56:57], off
	s_mov_b64 exec, s[50:51]
	s_branch .Lrw_nd_nopf
.Lrw_nd_pfslow:
	v_add_u32_e32 v30, s66, v93
	v_cmp_le_i32_e32 vcc, s59, v30
	v_cmp_ge_i32_e64 s[50:51], s58, v30
	s_and_b64 s[50:51], vcc, s[50:51]
	v_mov_b32_e32 v28, v164
	v_mov_b32_e32 v29, v164
	s_and_b64 s[68:69], s[42:43], s[50:51]
	v_mov_b64_e32 v[32:33], v[28:29]
	v_mov_b64_e32 v[34:35], v[28:29]
	s_and_saveexec_b64 s[50:51], s[68:69]
	s_cbranch_execz .LBB0_1471
	v_mov_b32_e32 v31, v164
	v_lshlrev_b64 v[30:31], 11, v[30:31]
	v_lshl_add_u64 v[30:31], v[84:85], 0, v[30:31]
	global_load_dwordx4 v[32:35], v[30:31], off
